# v18 + hyena filter MAC loop on the f32 matrix core (v_mfma_f32_4x4x1_16b_f32, f32 operands/accumulate, exact FMA): one MFMA + one ds_read_b32 per lag step instead of 4 FMAs + a broadcast ds_read_b128
# speedup vs baseline: 1.0118x; 1.0049x over previous
; DI void phase_filter(const Params& p, int ch) {
;     ...
;     for (int c4 = 0; c4 < 16; ++c4) {
;       float a0 = 0.f, a1 = 0.f, a2 = 0.f, a3 = 0.f;
; #pragma unroll
;       for (int j = 0; j < 64; ++j) { f32x4 w = *(const f32x4*)(w3s + j * 64 + c4 * 4); a0 += hv[j] * w[0]; a1 += hv[j] * w[1]; a2 += hv[j] * w[2]; a3 += hv[j] * w[3]; }
;       float av[4] = {a0, a1, a2, a3};
; #pragma unroll
;       for (int i = 0; i < 4; ++i) { int cl = c4 * 4 + i; float delta = fabsf(mind + (float)(c0 + cl) * ((maxd - mind) / 2047.f)); float k = av[i] * __expf(-tl * delta);
;         float* row = kr + (size_t)(cc0 + cl) * N;
;         if (dir == 0) row[l] = k; else if (l > 0) row[N - l] = k; else row[L] = 0.f; }
.LBB0_1410:
	v_and_b32_e32 v84, 3, v180
	v_lshl_add_u32 v84, v84, 2, s14
	ds_read_b32 v220, v84
	ds_read_b32 v221, v84 offset:256
	ds_read_b32 v222, v84 offset:512
	ds_read_b32 v223, v84 offset:768
	ds_read_b32 v224, v84 offset:1024
	ds_read_b32 v225, v84 offset:1280
	ds_read_b32 v226, v84 offset:1536
	ds_read_b32 v227, v84 offset:1792
	ds_read_b32 v228, v84 offset:2048
	ds_read_b32 v229, v84 offset:2304
	ds_read_b32 v230, v84 offset:2560
	ds_read_b32 v231, v84 offset:2816
	ds_read_b32 v232, v84 offset:3072
	s_add_i32 s15, s1, s20
	s_add_i32 s21, s37, s20
	s_lshl_b32 s96, s21, s0
	s_add_i32 s22, s15, 1
	s_waitcnt lgkmcnt(12)
	v_mfma_f32_4x4x1_16b_f32 v[236:239], v220, v6, 0
	ds_read_b32 v233, v84 offset:3328
	v_cvt_f32_u32_e32 v79, s15
	s_add_i32 s20, s20, 4
	s_waitcnt lgkmcnt(12)
	v_mfma_f32_4x4x1_16b_f32 v[244:247], v221, v7, 0
	ds_read_b32 v234, v84 offset:3584
	v_fmamk_f32 v79, v79, 0xbbc49550, v149
	v_mul_f32_e64 v79, v74, |v79|
	v_mul_f32_e32 v79, 0x3fb8aa3b, v79
	v_exp_f32_e32 v79, v79
	s_waitcnt lgkmcnt(12)
	v_mfma_f32_4x4x1_16b_f32 v[236:239], v222, v12, v[236:239]
	ds_read_b32 v235, v84 offset:3840
	s_add_i32 s14, s14, 16
	s_waitcnt lgkmcnt(12)
	v_mfma_f32_4x4x1_16b_f32 v[244:247], v223, v13, v[244:247]
	ds_read_b32 v220, v84 offset:4096
	s_waitcnt lgkmcnt(12)
	v_mfma_f32_4x4x1_16b_f32 v[236:239], v224, v14, v[236:239]
	ds_read_b32 v221, v84 offset:4352
	s_waitcnt lgkmcnt(12)
	v_mfma_f32_4x4x1_16b_f32 v[244:247], v225, v15, v[244:247]
	ds_read_b32 v222, v84 offset:4608
	s_waitcnt lgkmcnt(12)
	v_mfma_f32_4x4x1_16b_f32 v[236:239], v226, v16, v[236:239]
	ds_read_b32 v223, v84 offset:4864
	s_waitcnt lgkmcnt(12)
	v_mfma_f32_4x4x1_16b_f32 v[244:247], v227, v17, v[244:247]
	ds_read_b32 v224, v84 offset:5120
	s_waitcnt lgkmcnt(12)
	v_mfma_f32_4x4x1_16b_f32 v[236:239], v228, v18, v[236:239]
	ds_read_b32 v225, v84 offset:5376
	s_waitcnt lgkmcnt(12)
	v_mfma_f32_4x4x1_16b_f32 v[244:247], v229, v19, v[244:247]
	ds_read_b32 v226, v84 offset:5632
	s_waitcnt lgkmcnt(12)
	v_mfma_f32_4x4x1_16b_f32 v[236:239], v230, v20, v[236:239]
	ds_read_b32 v227, v84 offset:5888
	s_waitcnt lgkmcnt(12)
	v_mfma_f32_4x4x1_16b_f32 v[244:247], v231, v21, v[244:247]
	ds_read_b32 v228, v84 offset:6144
	s_waitcnt lgkmcnt(12)
	v_mfma_f32_4x4x1_16b_f32 v[236:239], v232, v22, v[236:239]
	ds_read_b32 v229, v84 offset:6400
	s_waitcnt lgkmcnt(12)
	v_mfma_f32_4x4x1_16b_f32 v[244:247], v233, v23, v[244:247]
	ds_read_b32 v230, v84 offset:6656
	s_waitcnt lgkmcnt(12)
	v_mfma_f32_4x4x1_16b_f32 v[236:239], v234, v24, v[236:239]
	ds_read_b32 v231, v84 offset:6912
	s_waitcnt lgkmcnt(12)
	v_mfma_f32_4x4x1_16b_f32 v[244:247], v235, v25, v[244:247]
	ds_read_b32 v232, v84 offset:7168
	s_waitcnt lgkmcnt(12)
	v_mfma_f32_4x4x1_16b_f32 v[236:239], v220, v26, v[236:239]
	ds_read_b32 v233, v84 offset:7424
	s_waitcnt lgkmcnt(12)
	v_mfma_f32_4x4x1_16b_f32 v[244:247], v221, v27, v[244:247]
	ds_read_b32 v234, v84 offset:7680
	s_waitcnt lgkmcnt(12)
	v_mfma_f32_4x4x1_16b_f32 v[236:239], v222, v28, v[236:239]
	ds_read_b32 v235, v84 offset:7936
	s_waitcnt lgkmcnt(12)
	v_mfma_f32_4x4x1_16b_f32 v[244:247], v223, v29, v[244:247]
	ds_read_b32 v220, v84 offset:8192
	s_waitcnt lgkmcnt(12)
	v_mfma_f32_4x4x1_16b_f32 v[236:239], v224, v30, v[236:239]
	ds_read_b32 v221, v84 offset:8448
	s_waitcnt lgkmcnt(12)
	v_mfma_f32_4x4x1_16b_f32 v[244:247], v225, v31, v[244:247]
	ds_read_b32 v222, v84 offset:8704
	s_waitcnt lgkmcnt(12)
	v_mfma_f32_4x4x1_16b_f32 v[236:239], v226, v32, v[236:239]
	ds_read_b32 v223, v84 offset:8960
	s_waitcnt lgkmcnt(12)
	v_mfma_f32_4x4x1_16b_f32 v[244:247], v227, v33, v[244:247]
	ds_read_b32 v224, v84 offset:9216
	s_waitcnt lgkmcnt(12)
	v_mfma_f32_4x4x1_16b_f32 v[236:239], v228, v34, v[236:239]
	ds_read_b32 v225, v84 offset:9472
	s_waitcnt lgkmcnt(12)
	v_mfma_f32_4x4x1_16b_f32 v[244:247], v229, v35, v[244:247]
	ds_read_b32 v226, v84 offset:9728
	s_waitcnt lgkmcnt(12)
	v_mfma_f32_4x4x1_16b_f32 v[236:239], v230, v36, v[236:239]
	ds_read_b32 v227, v84 offset:9984
	s_waitcnt lgkmcnt(12)
	v_mfma_f32_4x4x1_16b_f32 v[244:247], v231, v37, v[244:247]
	ds_read_b32 v228, v84 offset:10240
	s_waitcnt lgkmcnt(12)
	v_mfma_f32_4x4x1_16b_f32 v[236:239], v232, v38, v[236:239]
	ds_read_b32 v229, v84 offset:10496
	s_waitcnt lgkmcnt(12)
	v_mfma_f32_4x4x1_16b_f32 v[244:247], v233, v39, v[244:247]
	ds_read_b32 v230, v84 offset:10752
	s_waitcnt lgkmcnt(12)
	v_mfma_f32_4x4x1_16b_f32 v[236:239], v234, v40, v[236:239]
	ds_read_b32 v231, v84 offset:11008
	s_waitcnt lgkmcnt(12)
	v_mfma_f32_4x4x1_16b_f32 v[244:247], v235, v41, v[244:247]
	ds_read_b32 v232, v84 offset:11264
	s_waitcnt lgkmcnt(12)
	v_mfma_f32_4x4x1_16b_f32 v[236:239], v220, v42, v[236:239]
	ds_read_b32 v233, v84 offset:11520
	s_waitcnt lgkmcnt(12)
; DI void phase_filter(const Params& p, int ch) {
;     ...
;     for (int c4 = 0; c4 < 16; ++c4) {
;       float a0 = 0.f, a1 = 0.f, a2 = 0.f, a3 = 0.f;
; #pragma unroll
;       for (int j = 0; j < 64; ++j) { f32x4 w = *(const f32x4*)(w3s + j * 64 + c4 * 4); a0 += hv[j] * w[0]; a1 += hv[j] * w[1]; a2 += hv[j] * w[2]; a3 += hv[j] * w[3]; }
;       float av[4] = {a0, a1, a2, a3};
; #pragma unroll
;       for (int i = 0; i < 4; ++i) { int cl = c4 * 4 + i; float delta = fabsf(mind + (float)(c0 + cl) * ((maxd - mind) / 2047.f)); float k = av[i] * __expf(-tl * delta);
;         float* row = kr + (size_t)(cc0 + cl) * N;
;         if (dir == 0) row[l] = k; else if (l > 0) row[N - l] = k; else row[L] = 0.f; }
;     }
;     __syncthreads();
	v_mfma_f32_4x4x1_16b_f32 v[244:247], v221, v43, v[244:247]
	ds_read_b32 v234, v84 offset:11776
	s_waitcnt lgkmcnt(12)
	v_mfma_f32_4x4x1_16b_f32 v[236:239], v222, v44, v[236:239]
	ds_read_b32 v235, v84 offset:12032
	s_waitcnt lgkmcnt(12)
	v_mfma_f32_4x4x1_16b_f32 v[244:247], v223, v45, v[244:247]
	ds_read_b32 v220, v84 offset:12288
	s_waitcnt lgkmcnt(12)
	v_mfma_f32_4x4x1_16b_f32 v[236:239], v224, v46, v[236:239]
	ds_read_b32 v221, v84 offset:12544
	s_waitcnt lgkmcnt(12)
	v_mfma_f32_4x4x1_16b_f32 v[244:247], v225, v47, v[244:247]
	ds_read_b32 v222, v84 offset:12800
	s_waitcnt lgkmcnt(12)
	v_mfma_f32_4x4x1_16b_f32 v[236:239], v226, v48, v[236:239]
	ds_read_b32 v223, v84 offset:13056
	s_waitcnt lgkmcnt(12)
	v_mfma_f32_4x4x1_16b_f32 v[244:247], v227, v49, v[244:247]
	ds_read_b32 v224, v84 offset:13312
	s_waitcnt lgkmcnt(12)
	v_mfma_f32_4x4x1_16b_f32 v[236:239], v228, v50, v[236:239]
	ds_read_b32 v225, v84 offset:13568
	s_waitcnt lgkmcnt(12)
	v_mfma_f32_4x4x1_16b_f32 v[244:247], v229, v51, v[244:247]
	ds_read_b32 v226, v84 offset:13824
	s_waitcnt lgkmcnt(12)
	v_mfma_f32_4x4x1_16b_f32 v[236:239], v230, v52, v[236:239]
	ds_read_b32 v227, v84 offset:14080
	s_waitcnt lgkmcnt(12)
	v_mfma_f32_4x4x1_16b_f32 v[244:247], v231, v53, v[244:247]
	ds_read_b32 v228, v84 offset:14336
	s_waitcnt lgkmcnt(12)
	v_mfma_f32_4x4x1_16b_f32 v[236:239], v232, v54, v[236:239]
	ds_read_b32 v229, v84 offset:14592
	s_waitcnt lgkmcnt(12)
	v_mfma_f32_4x4x1_16b_f32 v[244:247], v233, v55, v[244:247]
	ds_read_b32 v230, v84 offset:14848
	s_waitcnt lgkmcnt(12)
	v_mfma_f32_4x4x1_16b_f32 v[236:239], v234, v56, v[236:239]
	ds_read_b32 v231, v84 offset:15104
	s_waitcnt lgkmcnt(12)
	v_mfma_f32_4x4x1_16b_f32 v[244:247], v235, v57, v[244:247]
	ds_read_b32 v232, v84 offset:15360
	s_waitcnt lgkmcnt(12)
	v_mfma_f32_4x4x1_16b_f32 v[236:239], v220, v58, v[236:239]
	ds_read_b32 v233, v84 offset:15616
	s_waitcnt lgkmcnt(12)
	v_mfma_f32_4x4x1_16b_f32 v[244:247], v221, v59, v[244:247]
	ds_read_b32 v234, v84 offset:15872
	s_waitcnt lgkmcnt(12)
	v_mfma_f32_4x4x1_16b_f32 v[236:239], v222, v60, v[236:239]
	ds_read_b32 v235, v84 offset:16128
	s_waitcnt lgkmcnt(12)
	v_mfma_f32_4x4x1_16b_f32 v[244:247], v223, v61, v[244:247]
	s_waitcnt lgkmcnt(11)
	v_mfma_f32_4x4x1_16b_f32 v[236:239], v224, v62, v[236:239]
	s_waitcnt lgkmcnt(10)
	v_mfma_f32_4x4x1_16b_f32 v[244:247], v225, v63, v[244:247]
	s_waitcnt lgkmcnt(9)
	v_mfma_f32_4x4x1_16b_f32 v[236:239], v226, v64, v[236:239]
	s_waitcnt lgkmcnt(8)
	v_mfma_f32_4x4x1_16b_f32 v[244:247], v227, v65, v[244:247]
	s_waitcnt lgkmcnt(7)
	v_mfma_f32_4x4x1_16b_f32 v[236:239], v228, v66, v[236:239]
	s_waitcnt lgkmcnt(6)
	v_mfma_f32_4x4x1_16b_f32 v[244:247], v229, v67, v[244:247]
	s_waitcnt lgkmcnt(5)
	v_mfma_f32_4x4x1_16b_f32 v[236:239], v230, v68, v[236:239]
	s_waitcnt lgkmcnt(4)
	v_mfma_f32_4x4x1_16b_f32 v[244:247], v231, v69, v[244:247]
	s_waitcnt lgkmcnt(3)
	v_mfma_f32_4x4x1_16b_f32 v[236:239], v232, v70, v[236:239]
	s_waitcnt lgkmcnt(2)
	v_mfma_f32_4x4x1_16b_f32 v[244:247], v233, v71, v[244:247]
	s_waitcnt lgkmcnt(1)
	v_mfma_f32_4x4x1_16b_f32 v[236:239], v234, v72, v[236:239]
	s_waitcnt lgkmcnt(0)
	v_mfma_f32_4x4x1_16b_f32 v[244:247], v235, v73, v[244:247]
	s_nop 5
	v_add_f32_e32 v78, v236, v244
	v_add_f32_e32 v77, v237, v245
	v_add_f32_e32 v76, v238, v246
	v_add_f32_e32 v75, v239, v247
	v_mul_f32_e32 v78, v79, v78
	v_cndmask_b32_e32 v80, 0, v78, vcc
	v_lshl_add_u64 v[78:79], s[96:97], 2, v[4:5]
	global_store_dword v[78:79], v80, off
	v_cvt_f32_u32_e32 v78, s22
	s_add_i32 s22, s21, 1
	s_lshl_b32 s96, s22, s0
	v_fmamk_f32 v78, v78, 0xbbc49550, v149
	v_mul_f32_e64 v78, v74, |v78|
	v_mul_f32_e32 v78, 0x3fb8aa3b, v78
	v_exp_f32_e32 v78, v78
	s_add_i32 s22, s15, 2
	s_add_i32 s15, s15, 3
	v_mul_f32_e32 v77, v78, v77
	v_cndmask_b32_e32 v77, 0, v77, vcc
	v_lshl_add_u64 v[78:79], s[96:97], 2, v[4:5]
	global_store_dword v[78:79], v77, off
	v_cvt_f32_u32_e32 v77, s22
	s_add_i32 s22, s21, 2
	s_lshl_b32 s96, s22, s0
	v_fmamk_f32 v77, v77, 0xbbc49550, v149
	v_mul_f32_e64 v77, v74, |v77|
	v_mul_f32_e32 v77, 0x3fb8aa3b, v77
	v_exp_f32_e32 v77, v77
	s_add_i32 s21, s21, 3
	v_mul_f32_e32 v76, v77, v76
	v_cndmask_b32_e32 v78, 0, v76, vcc
	v_lshl_add_u64 v[76:77], s[96:97], 2, v[4:5]
	global_store_dword v[76:77], v78, off
	v_cvt_f32_u32_e32 v76, s15
	s_lshl_b32 s96, s21, s0
	s_cmp_lg_u32 s20, 64
	v_fmamk_f32 v76, v76, 0xbbc49550, v149
	v_mul_f32_e64 v76, v74, |v76|
	v_mul_f32_e32 v76, 0x3fb8aa3b, v76
	v_exp_f32_e32 v76, v76
	s_nop 0
	v_mul_f32_e32 v75, v76, v75
	v_cndmask_b32_e32 v75, 0, v75, vcc
	v_lshl_add_u64 v[76:77], s[96:97], 2, v[4:5]
	global_store_dword v[76:77], v75, off
	s_cbranch_scc1 .LBB0_1410
	s_add_i32 s36, s36, s28
	s_cmpk_lt_i32 s36, 0xc0
	s_barrier
	s_cbranch_scc1 .LBB0_1399
	v_readlane_b32 s38, v240, 53
	v_readlane_b32 s39, v240, 54
	s_mov_b32 s36, s70

; DI void bfly_fwd(float2 a0, float2 a1, float2 a2, float2 a3, float r, float2& o0, float2& o1, float2& o2, float2& o3) {
;   float2 t0 = {a0.x + a2.x, a0.y + a2.y}, t1 = {a0.x - a2.x, a0.y - a2.y}, t2 = {a1.x + a3.x, a1.y + a3.y}, t3 = {a1.x - a3.x, a1.y - a3.y};
;   float2 b0 = {t0.x + t2.x, t0.y + t2.y}, b2 = {t0.x - t2.x, t0.y - t2.y}, b1 = {t1.x + t3.y, t1.y - t3.x}, b3 = {t1.x - t3.y, t1.y + t3.x};
;   const int Q = 1 << lq; const float invM = 1.f / (float)(4 << lq);
;   for (int bb = tid; bb < NBT * (N / 4); bb += NTHR) { const int b = bb & (N / 4 - 1); float2* z = z0 + (bb / (N / 4)) * N; int j = b & (Q - 1), base = ((b >> lq) << (lq + 2)) + j; float2 o0, o1, o2, o3;
;     bfly_fwd(z[base], z[base + Q], z[base + 2 * Q], z[base + 3 * Q], (float)j * invM, o0, o1, o2, o3);
;     z[base] = o0; z[base + Q] = o1; z[base + 2 * Q] = o2; z[base + 3 * Q] = o3; }
;   __syncthreads();
; }
.LBB0_1499:
	v_ashrrev_i32_e32 v13, 31, v12
	v_lshrrev_b32_e32 v13, 21, v13
	v_add_lshl_u32 v13, v12, v13, 5
	v_and_b32_e32 v14, 0x1ffc, v11
	v_and_b32_e32 v13, 0xffff0000, v13
	v_lshlrev_b32_e32 v14, 3, v14
	v_add3_u32 v13, 16, v13, v14
	v_add_u32_e32 v204, 0x10000, v13
	ds_read_b128 v[14:17], v13
	ds_read_b128 v[18:21], v13 offset:16
	ds_read_b128 v[188:191], v13 offset:16384
	ds_read_b128 v[192:195], v13 offset:16400
	ds_read_b128 v[196:199], v13 offset:32768
	ds_read_b128 v[200:203], v13 offset:32784
	s_waitcnt lgkmcnt(4)
	v_pk_add_f32 v[22:23], v[14:15], v[18:19]
	v_pk_add_f32 v[26:27], v[16:17], v[20:21]
	v_pk_add_f32 v[24:25], v[14:15], v[18:19] neg_lo:[0,1] neg_hi:[0,1]
	v_pk_add_f32 v[28:29], v[16:17], v[20:21] neg_lo:[0,1] neg_hi:[0,1]
	v_pk_add_f32 v[14:15], v[22:23], v[26:27]
	v_pk_add_f32 v[18:19], v[22:23], v[26:27] neg_lo:[0,1] neg_hi:[0,1]
	v_pk_add_f32 v[16:17], v[24:25], v[28:29] op_sel:[0,1] op_sel_hi:[1,0] neg_hi:[0,1]
	v_pk_add_f32 v[20:21], v[24:25], v[28:29] op_sel:[0,1] op_sel_hi:[1,0] neg_lo:[0,1]
	s_nop 0
	ds_write_b128 v13, v[14:17]
	ds_write_b128 v13, v[18:21] offset:16
	ds_read_b128 v[14:17], v13 offset:49152
	ds_read_b128 v[18:21], v13 offset:49168
	s_waitcnt lgkmcnt(6)
	v_pk_add_f32 v[22:23], v[188:189], v[192:193]
	v_pk_add_f32 v[26:27], v[190:191], v[194:195]
	v_pk_add_f32 v[24:25], v[188:189], v[192:193] neg_lo:[0,1] neg_hi:[0,1]
	v_pk_add_f32 v[28:29], v[190:191], v[194:195] neg_lo:[0,1] neg_hi:[0,1]
	v_pk_add_f32 v[188:189], v[22:23], v[26:27]
	v_pk_add_f32 v[192:193], v[22:23], v[26:27] neg_lo:[0,1] neg_hi:[0,1]
	v_pk_add_f32 v[190:191], v[24:25], v[28:29] op_sel:[0,1] op_sel_hi:[1,0] neg_hi:[0,1]
	v_pk_add_f32 v[194:195], v[24:25], v[28:29] op_sel:[0,1] op_sel_hi:[1,0] neg_lo:[0,1]
	s_nop 0
	ds_write_b128 v13, v[188:191] offset:16384
	ds_write_b128 v13, v[192:195] offset:16400
	s_waitcnt lgkmcnt(6)
	v_pk_add_f32 v[22:23], v[196:197], v[200:201]
	v_pk_add_f32 v[26:27], v[198:199], v[202:203]
	v_pk_add_f32 v[24:25], v[196:197], v[200:201] neg_lo:[0,1] neg_hi:[0,1]
	v_pk_add_f32 v[28:29], v[198:199], v[202:203] neg_lo:[0,1] neg_hi:[0,1]
	v_pk_add_f32 v[196:197], v[22:23], v[26:27]
	v_pk_add_f32 v[200:201], v[22:23], v[26:27] neg_lo:[0,1] neg_hi:[0,1]
	v_pk_add_f32 v[198:199], v[24:25], v[28:29] op_sel:[0,1] op_sel_hi:[1,0] neg_hi:[0,1]
	v_pk_add_f32 v[202:203], v[24:25], v[28:29] op_sel:[0,1] op_sel_hi:[1,0] neg_lo:[0,1]
	s_nop 0
	ds_write_b128 v13, v[196:199] offset:32768
	ds_write_b128 v13, v[200:203] offset:32784
	s_waitcnt lgkmcnt(4)
	v_pk_add_f32 v[22:23], v[14:15], v[18:19]
	v_pk_add_f32 v[26:27], v[16:17], v[20:21]
	v_pk_add_f32 v[24:25], v[14:15], v[18:19] neg_lo:[0,1] neg_hi:[0,1]
	v_pk_add_f32 v[28:29], v[16:17], v[20:21] neg_lo:[0,1] neg_hi:[0,1]
	v_pk_add_f32 v[14:15], v[22:23], v[26:27]
	v_pk_add_f32 v[18:19], v[22:23], v[26:27] neg_lo:[0,1] neg_hi:[0,1]
	v_pk_add_f32 v[16:17], v[24:25], v[28:29] op_sel:[0,1] op_sel_hi:[1,0] neg_hi:[0,1]
	v_pk_add_f32 v[20:21], v[24:25], v[28:29] op_sel:[0,1] op_sel_hi:[1,0] neg_lo:[0,1]
	s_nop 0
	ds_write_b128 v13, v[14:17] offset:49152
	ds_write_b128 v13, v[18:21] offset:49168
	v_add_u32_e32 v11, 0x2000, v11
	v_add_u32_e32 v13, 0x800, v12
	v_mov_b32_e32 v12, v13
	s_mov_b64 s[8:9], exec

; DI void bfly_fwd(float2 a0, float2 a1, float2 a2, float2 a3, float r, float2& o0, float2& o1, float2& o2, float2& o3) {
;   float2 t0 = {a0.x + a2.x, a0.y + a2.y}, t1 = {a0.x - a2.x, a0.y - a2.y}, t2 = {a1.x + a3.x, a1.y + a3.y}, t3 = {a1.x - a3.x, a1.y - a3.y};
;   float2 b0 = {t0.x + t2.x, t0.y + t2.y}, b2 = {t0.x - t2.x, t0.y - t2.y}, b1 = {t1.x + t3.y, t1.y - t3.x}, b3 = {t1.x - t3.y, t1.y + t3.x};
;   const int Q = 1 << lq; const float invM = 1.f / (float)(4 << lq);
;   for (int bb = tid; bb < NBT * (N / 4); bb += NTHR) { const int b = bb & (N / 4 - 1); float2* z = z0 + (bb / (N / 4)) * N; int j = b & (Q - 1), base = ((b >> lq) << (lq + 2)) + j; float2 o0, o1, o2, o3;
;     bfly_fwd(z[base], z[base + Q], z[base + 2 * Q], z[base + 3 * Q], (float)j * invM, o0, o1, o2, o3);
;     z[base] = o0; z[base + Q] = o1; z[base + 2 * Q] = o2; z[base + 3 * Q] = o3; }
;   __syncthreads();
; }
.LBB0_1527:
	v_ashrrev_i32_e32 v13, 31, v12
	v_lshrrev_b32_e32 v13, 20, v13
	v_add_lshl_u32 v13, v12, v13, 5
	v_and_b32_e32 v14, 0x3ffc, v11
	v_and_b32_e32 v13, 0xfffe0000, v13
	v_lshlrev_b32_e32 v14, 3, v14
	v_add3_u32 v13, 16, v13, v14
	v_add_u32_e32 v204, 0x10000, v13
	ds_read_b128 v[14:17], v13
	ds_read_b128 v[18:21], v13 offset:16
	ds_read_b128 v[188:191], v13 offset:16384
	ds_read_b128 v[192:195], v13 offset:16400
	ds_read_b128 v[196:199], v13 offset:32768
	ds_read_b128 v[200:203], v13 offset:32784
	s_waitcnt lgkmcnt(4)
	v_pk_add_f32 v[22:23], v[14:15], v[18:19]
	v_pk_add_f32 v[26:27], v[16:17], v[20:21]
	v_pk_add_f32 v[24:25], v[14:15], v[18:19] neg_lo:[0,1] neg_hi:[0,1]
	v_pk_add_f32 v[28:29], v[16:17], v[20:21] neg_lo:[0,1] neg_hi:[0,1]
	v_pk_add_f32 v[14:15], v[22:23], v[26:27]
	v_pk_add_f32 v[18:19], v[22:23], v[26:27] neg_lo:[0,1] neg_hi:[0,1]
	v_pk_add_f32 v[16:17], v[24:25], v[28:29] op_sel:[0,1] op_sel_hi:[1,0] neg_hi:[0,1]
	v_pk_add_f32 v[20:21], v[24:25], v[28:29] op_sel:[0,1] op_sel_hi:[1,0] neg_lo:[0,1]
	s_nop 0
	ds_write_b128 v13, v[14:17]
	ds_write_b128 v13, v[18:21] offset:16
	ds_read_b128 v[14:17], v13 offset:49152
	ds_read_b128 v[18:21], v13 offset:49168
	s_waitcnt lgkmcnt(6)
	v_pk_add_f32 v[22:23], v[188:189], v[192:193]
	v_pk_add_f32 v[26:27], v[190:191], v[194:195]
	v_pk_add_f32 v[24:25], v[188:189], v[192:193] neg_lo:[0,1] neg_hi:[0,1]
	v_pk_add_f32 v[28:29], v[190:191], v[194:195] neg_lo:[0,1] neg_hi:[0,1]
	v_pk_add_f32 v[188:189], v[22:23], v[26:27]
	v_pk_add_f32 v[192:193], v[22:23], v[26:27] neg_lo:[0,1] neg_hi:[0,1]
	v_pk_add_f32 v[190:191], v[24:25], v[28:29] op_sel:[0,1] op_sel_hi:[1,0] neg_hi:[0,1]
	v_pk_add_f32 v[194:195], v[24:25], v[28:29] op_sel:[0,1] op_sel_hi:[1,0] neg_lo:[0,1]
	s_nop 0
	ds_write_b128 v13, v[188:191] offset:16384
	ds_write_b128 v13, v[192:195] offset:16400
	ds_read_b128 v[188:191], v204
	ds_read_b128 v[192:195], v204 offset:16
	s_waitcnt lgkmcnt(8)
	v_pk_add_f32 v[22:23], v[196:197], v[200:201]
	v_pk_add_f32 v[26:27], v[198:199], v[202:203]
	v_pk_add_f32 v[24:25], v[196:197], v[200:201] neg_lo:[0,1] neg_hi:[0,1]
	v_pk_add_f32 v[28:29], v[198:199], v[202:203] neg_lo:[0,1] neg_hi:[0,1]
	v_pk_add_f32 v[196:197], v[22:23], v[26:27]
	v_pk_add_f32 v[200:201], v[22:23], v[26:27] neg_lo:[0,1] neg_hi:[0,1]
	v_pk_add_f32 v[198:199], v[24:25], v[28:29] op_sel:[0,1] op_sel_hi:[1,0] neg_hi:[0,1]
	v_pk_add_f32 v[202:203], v[24:25], v[28:29] op_sel:[0,1] op_sel_hi:[1,0] neg_lo:[0,1]
	s_nop 0
	ds_write_b128 v13, v[196:199] offset:32768
	ds_write_b128 v13, v[200:203] offset:32784
	ds_read_b128 v[196:199], v204 offset:16384
	ds_read_b128 v[200:203], v204 offset:16400
	s_waitcnt lgkmcnt(8)
	v_pk_add_f32 v[22:23], v[14:15], v[18:19]
	v_pk_add_f32 v[26:27], v[16:17], v[20:21]
	v_pk_add_f32 v[24:25], v[14:15], v[18:19] neg_lo:[0,1] neg_hi:[0,1]
	v_pk_add_f32 v[28:29], v[16:17], v[20:21] neg_lo:[0,1] neg_hi:[0,1]
	v_pk_add_f32 v[14:15], v[22:23], v[26:27]
	v_pk_add_f32 v[18:19], v[22:23], v[26:27] neg_lo:[0,1] neg_hi:[0,1]
	v_pk_add_f32 v[16:17], v[24:25], v[28:29] op_sel:[0,1] op_sel_hi:[1,0] neg_hi:[0,1]
	v_pk_add_f32 v[20:21], v[24:25], v[28:29] op_sel:[0,1] op_sel_hi:[1,0] neg_lo:[0,1]
	s_nop 0
	ds_write_b128 v13, v[14:17] offset:49152
	ds_write_b128 v13, v[18:21] offset:49168
	ds_read_b128 v[14:17], v204 offset:32768
	ds_read_b128 v[18:21], v204 offset:32784
	s_waitcnt lgkmcnt(8)
	v_pk_add_f32 v[22:23], v[188:189], v[192:193]
	v_pk_add_f32 v[26:27], v[190:191], v[194:195]
	v_pk_add_f32 v[24:25], v[188:189], v[192:193] neg_lo:[0,1] neg_hi:[0,1]
	v_pk_add_f32 v[28:29], v[190:191], v[194:195] neg_lo:[0,1] neg_hi:[0,1]
	v_pk_add_f32 v[188:189], v[22:23], v[26:27]
	v_pk_add_f32 v[192:193], v[22:23], v[26:27] neg_lo:[0,1] neg_hi:[0,1]
	v_pk_add_f32 v[190:191], v[24:25], v[28:29] op_sel:[0,1] op_sel_hi:[1,0] neg_hi:[0,1]
	v_pk_add_f32 v[194:195], v[24:25], v[28:29] op_sel:[0,1] op_sel_hi:[1,0] neg_lo:[0,1]
	s_nop 0
	ds_write_b128 v204, v[188:191]
	ds_write_b128 v204, v[192:195] offset:16
	ds_read_b128 v[188:191], v204 offset:49152
	ds_read_b128 v[192:195], v204 offset:49168
	s_waitcnt lgkmcnt(8)
	v_pk_add_f32 v[22:23], v[196:197], v[200:201]
	v_pk_add_f32 v[26:27], v[198:199], v[202:203]
	v_pk_add_f32 v[24:25], v[196:197], v[200:201] neg_lo:[0,1] neg_hi:[0,1]
	v_pk_add_f32 v[28:29], v[198:199], v[202:203] neg_lo:[0,1] neg_hi:[0,1]
	v_pk_add_f32 v[196:197], v[22:23], v[26:27]
	v_pk_add_f32 v[200:201], v[22:23], v[26:27] neg_lo:[0,1] neg_hi:[0,1]
	v_pk_add_f32 v[198:199], v[24:25], v[28:29] op_sel:[0,1] op_sel_hi:[1,0] neg_hi:[0,1]
	v_pk_add_f32 v[202:203], v[24:25], v[28:29] op_sel:[0,1] op_sel_hi:[1,0] neg_lo:[0,1]
	s_nop 0
	ds_write_b128 v204, v[196:199] offset:16384
	ds_write_b128 v204, v[200:203] offset:16400
	s_waitcnt lgkmcnt(6)
	v_pk_add_f32 v[22:23], v[14:15], v[18:19]
	v_pk_add_f32 v[26:27], v[16:17], v[20:21]
	v_pk_add_f32 v[24:25], v[14:15], v[18:19] neg_lo:[0,1] neg_hi:[0,1]
	v_pk_add_f32 v[28:29], v[16:17], v[20:21] neg_lo:[0,1] neg_hi:[0,1]
	v_pk_add_f32 v[14:15], v[22:23], v[26:27]
	v_pk_add_f32 v[18:19], v[22:23], v[26:27] neg_lo:[0,1] neg_hi:[0,1]
	v_pk_add_f32 v[16:17], v[24:25], v[28:29] op_sel:[0,1] op_sel_hi:[1,0] neg_hi:[0,1]
	v_pk_add_f32 v[20:21], v[24:25], v[28:29] op_sel:[0,1] op_sel_hi:[1,0] neg_lo:[0,1]
	s_nop 0
	ds_write_b128 v204, v[14:17] offset:32768
	ds_write_b128 v204, v[18:21] offset:32784
	s_waitcnt lgkmcnt(4)
	v_pk_add_f32 v[22:23], v[188:189], v[192:193]
	v_pk_add_f32 v[26:27], v[190:191], v[194:195]
	v_pk_add_f32 v[24:25], v[188:189], v[192:193] neg_lo:[0,1] neg_hi:[0,1]
	v_pk_add_f32 v[28:29], v[190:191], v[194:195] neg_lo:[0,1] neg_hi:[0,1]
	v_pk_add_f32 v[188:189], v[22:23], v[26:27]
	v_pk_add_f32 v[192:193], v[22:23], v[26:27] neg_lo:[0,1] neg_hi:[0,1]
	v_pk_add_f32 v[190:191], v[24:25], v[28:29] op_sel:[0,1] op_sel_hi:[1,0] neg_hi:[0,1]
	v_pk_add_f32 v[194:195], v[24:25], v[28:29] op_sel:[0,1] op_sel_hi:[1,0] neg_lo:[0,1]
	s_nop 0
	ds_write_b128 v204, v[188:191] offset:49152
	ds_write_b128 v204, v[192:195] offset:49168
	v_add_u32_e32 v11, 0x4000, v11
	v_add_u32_e32 v13, 0x1000, v12
	v_mov_b32_e32 v12, v13
	s_mov_b64 s[8:9], exec

; DI void bfly_fwd(float2 a0, float2 a1, float2 a2, float2 a3, float r, float2& o0, float2& o1, float2& o2, float2& o3) {
;   float2 t0 = {a0.x + a2.x, a0.y + a2.y}, t1 = {a0.x - a2.x, a0.y - a2.y}, t2 = {a1.x + a3.x, a1.y + a3.y}, t3 = {a1.x - a3.x, a1.y - a3.y};
;   float2 b0 = {t0.x + t2.x, t0.y + t2.y}, b2 = {t0.x - t2.x, t0.y - t2.y}, b1 = {t1.x + t3.y, t1.y - t3.x}, b3 = {t1.x - t3.y, t1.y + t3.x};
;   const int Q = 1 << lq; const float invM = 1.f / (float)(4 << lq);
;   for (int bb = tid; bb < NBT * (N / 4); bb += NTHR) { const int b = bb & (N / 4 - 1); float2* z = z0 + (bb / (N / 4)) * N; int j = b & (Q - 1), base = ((b >> lq) << (lq + 2)) + j; float2 o0, o1, o2, o3;
;     bfly_fwd(z[base], z[base + Q], z[base + 2 * Q], z[base + 3 * Q], (float)j * invM, o0, o1, o2, o3);
;     z[base] = o0; z[base + Q] = o1; z[base + 2 * Q] = o2; z[base + 3 * Q] = o3; }
;   __syncthreads();
; }
.LBB0_1609:
	v_ashrrev_i32_e32 v4, 31, v3
	v_lshrrev_b32_e32 v4, 21, v4
	v_add_lshl_u32 v4, v3, v4, 5
	v_and_b32_e32 v5, 0x1ffc, v2
	v_and_b32_e32 v4, 0xffff0000, v4
	v_lshlrev_b32_e32 v5, 3, v5
	v_add3_u32 v17, 16, v4, v5
	v_add_u32_e32 v204, 0x10000, v17
	ds_read_b128 v[4:7], v17
	ds_read_b128 v[8:11], v17 offset:16
	ds_read_b128 v[188:191], v17 offset:16384
	ds_read_b128 v[192:195], v17 offset:16400
	ds_read_b128 v[196:199], v17 offset:32768
	ds_read_b128 v[200:203], v17 offset:32784
	s_waitcnt lgkmcnt(4)
	v_pk_add_f32 v[12:13], v[4:5], v[8:9]
	v_pk_add_f32 v[20:21], v[6:7], v[10:11]
	v_pk_add_f32 v[18:19], v[4:5], v[8:9] neg_lo:[0,1] neg_hi:[0,1]
	v_pk_add_f32 v[22:23], v[6:7], v[10:11] neg_lo:[0,1] neg_hi:[0,1]
	v_pk_add_f32 v[4:5], v[12:13], v[20:21]
	v_pk_add_f32 v[8:9], v[12:13], v[20:21] neg_lo:[0,1] neg_hi:[0,1]
	v_pk_add_f32 v[6:7], v[18:19], v[22:23] op_sel:[0,1] op_sel_hi:[1,0] neg_hi:[0,1]
	v_pk_add_f32 v[10:11], v[18:19], v[22:23] op_sel:[0,1] op_sel_hi:[1,0] neg_lo:[0,1]
	s_nop 0
	ds_write_b128 v17, v[4:7]
	ds_write_b128 v17, v[8:11] offset:16
	ds_read_b128 v[4:7], v17 offset:49152
	ds_read_b128 v[8:11], v17 offset:49168
	s_waitcnt lgkmcnt(6)
	v_pk_add_f32 v[12:13], v[188:189], v[192:193]
	v_pk_add_f32 v[20:21], v[190:191], v[194:195]
	v_pk_add_f32 v[18:19], v[188:189], v[192:193] neg_lo:[0,1] neg_hi:[0,1]
	v_pk_add_f32 v[22:23], v[190:191], v[194:195] neg_lo:[0,1] neg_hi:[0,1]
	v_pk_add_f32 v[188:189], v[12:13], v[20:21]
	v_pk_add_f32 v[192:193], v[12:13], v[20:21] neg_lo:[0,1] neg_hi:[0,1]
	v_pk_add_f32 v[190:191], v[18:19], v[22:23] op_sel:[0,1] op_sel_hi:[1,0] neg_hi:[0,1]
	v_pk_add_f32 v[194:195], v[18:19], v[22:23] op_sel:[0,1] op_sel_hi:[1,0] neg_lo:[0,1]
	s_nop 0
	ds_write_b128 v17, v[188:191] offset:16384
	ds_write_b128 v17, v[192:195] offset:16400
	ds_read_b128 v[188:191], v204
	ds_read_b128 v[192:195], v204 offset:16
	s_waitcnt lgkmcnt(8)
	v_pk_add_f32 v[12:13], v[196:197], v[200:201]
	v_pk_add_f32 v[20:21], v[198:199], v[202:203]
	v_pk_add_f32 v[18:19], v[196:197], v[200:201] neg_lo:[0,1] neg_hi:[0,1]
	v_pk_add_f32 v[22:23], v[198:199], v[202:203] neg_lo:[0,1] neg_hi:[0,1]
	v_pk_add_f32 v[196:197], v[12:13], v[20:21]
	v_pk_add_f32 v[200:201], v[12:13], v[20:21] neg_lo:[0,1] neg_hi:[0,1]
	v_pk_add_f32 v[198:199], v[18:19], v[22:23] op_sel:[0,1] op_sel_hi:[1,0] neg_hi:[0,1]
	v_pk_add_f32 v[202:203], v[18:19], v[22:23] op_sel:[0,1] op_sel_hi:[1,0] neg_lo:[0,1]
	s_nop 0
	ds_write_b128 v17, v[196:199] offset:32768
	ds_write_b128 v17, v[200:203] offset:32784
	ds_read_b128 v[196:199], v204 offset:16384
	ds_read_b128 v[200:203], v204 offset:16400
	s_waitcnt lgkmcnt(8)
	v_pk_add_f32 v[12:13], v[4:5], v[8:9]
	v_pk_add_f32 v[20:21], v[6:7], v[10:11]
	v_pk_add_f32 v[18:19], v[4:5], v[8:9] neg_lo:[0,1] neg_hi:[0,1]
	v_pk_add_f32 v[22:23], v[6:7], v[10:11] neg_lo:[0,1] neg_hi:[0,1]
	v_pk_add_f32 v[4:5], v[12:13], v[20:21]
	v_pk_add_f32 v[8:9], v[12:13], v[20:21] neg_lo:[0,1] neg_hi:[0,1]
	v_pk_add_f32 v[6:7], v[18:19], v[22:23] op_sel:[0,1] op_sel_hi:[1,0] neg_hi:[0,1]
	v_pk_add_f32 v[10:11], v[18:19], v[22:23] op_sel:[0,1] op_sel_hi:[1,0] neg_lo:[0,1]
	s_nop 0
	ds_write_b128 v17, v[4:7] offset:49152
	ds_write_b128 v17, v[8:11] offset:49168
	ds_read_b128 v[4:7], v204 offset:32768
	ds_read_b128 v[8:11], v204 offset:32784
	s_waitcnt lgkmcnt(8)
	v_pk_add_f32 v[12:13], v[188:189], v[192:193]
	v_pk_add_f32 v[20:21], v[190:191], v[194:195]
	v_pk_add_f32 v[18:19], v[188:189], v[192:193] neg_lo:[0,1] neg_hi:[0,1]
	v_pk_add_f32 v[22:23], v[190:191], v[194:195] neg_lo:[0,1] neg_hi:[0,1]
	v_pk_add_f32 v[188:189], v[12:13], v[20:21]
	v_pk_add_f32 v[192:193], v[12:13], v[20:21] neg_lo:[0,1] neg_hi:[0,1]
	v_pk_add_f32 v[190:191], v[18:19], v[22:23] op_sel:[0,1] op_sel_hi:[1,0] neg_hi:[0,1]
	v_pk_add_f32 v[194:195], v[18:19], v[22:23] op_sel:[0,1] op_sel_hi:[1,0] neg_lo:[0,1]
	s_nop 0
	ds_write_b128 v204, v[188:191]
	ds_write_b128 v204, v[192:195] offset:16
	ds_read_b128 v[188:191], v204 offset:49152
	ds_read_b128 v[192:195], v204 offset:49168
	s_waitcnt lgkmcnt(8)
	v_pk_add_f32 v[12:13], v[196:197], v[200:201]
	v_pk_add_f32 v[20:21], v[198:199], v[202:203]
	v_pk_add_f32 v[18:19], v[196:197], v[200:201] neg_lo:[0,1] neg_hi:[0,1]
	v_pk_add_f32 v[22:23], v[198:199], v[202:203] neg_lo:[0,1] neg_hi:[0,1]
	v_pk_add_f32 v[196:197], v[12:13], v[20:21]
	v_pk_add_f32 v[200:201], v[12:13], v[20:21] neg_lo:[0,1] neg_hi:[0,1]
	v_pk_add_f32 v[198:199], v[18:19], v[22:23] op_sel:[0,1] op_sel_hi:[1,0] neg_hi:[0,1]
	v_pk_add_f32 v[202:203], v[18:19], v[22:23] op_sel:[0,1] op_sel_hi:[1,0] neg_lo:[0,1]
	s_nop 0
	ds_write_b128 v204, v[196:199] offset:16384
	ds_write_b128 v204, v[200:203] offset:16400
	s_waitcnt lgkmcnt(6)
	v_pk_add_f32 v[12:13], v[4:5], v[8:9]
	v_pk_add_f32 v[20:21], v[6:7], v[10:11]
	v_pk_add_f32 v[18:19], v[4:5], v[8:9] neg_lo:[0,1] neg_hi:[0,1]
	v_pk_add_f32 v[22:23], v[6:7], v[10:11] neg_lo:[0,1] neg_hi:[0,1]
	v_pk_add_f32 v[4:5], v[12:13], v[20:21]
	v_pk_add_f32 v[8:9], v[12:13], v[20:21] neg_lo:[0,1] neg_hi:[0,1]
	v_pk_add_f32 v[6:7], v[18:19], v[22:23] op_sel:[0,1] op_sel_hi:[1,0] neg_hi:[0,1]
	v_pk_add_f32 v[10:11], v[18:19], v[22:23] op_sel:[0,1] op_sel_hi:[1,0] neg_lo:[0,1]
	s_nop 0
	ds_write_b128 v204, v[4:7] offset:32768
	ds_write_b128 v204, v[8:11] offset:32784
	s_waitcnt lgkmcnt(4)
	v_pk_add_f32 v[12:13], v[188:189], v[192:193]
	v_pk_add_f32 v[20:21], v[190:191], v[194:195]
	v_pk_add_f32 v[18:19], v[188:189], v[192:193] neg_lo:[0,1] neg_hi:[0,1]
	v_pk_add_f32 v[22:23], v[190:191], v[194:195] neg_lo:[0,1] neg_hi:[0,1]
	v_pk_add_f32 v[188:189], v[12:13], v[20:21]
	v_pk_add_f32 v[192:193], v[12:13], v[20:21] neg_lo:[0,1] neg_hi:[0,1]
	v_pk_add_f32 v[190:191], v[18:19], v[22:23] op_sel:[0,1] op_sel_hi:[1,0] neg_hi:[0,1]
	v_pk_add_f32 v[194:195], v[18:19], v[22:23] op_sel:[0,1] op_sel_hi:[1,0] neg_lo:[0,1]
	s_nop 0
	ds_write_b128 v204, v[188:191] offset:49152
	ds_write_b128 v204, v[192:195] offset:49168
	v_add_u32_e32 v2, 0x4000, v2
	v_add_u32_e32 v4, 0x1000, v3
	v_mov_b32_e32 v3, v4
	s_mov_b64 s[80:81], exec

; DI void bfly_fwd(float2 a0, float2 a1, float2 a2, float2 a3, float r, float2& o0, float2& o1, float2& o2, float2& o3) {
;   float2 t0 = {a0.x + a2.x, a0.y + a2.y}, t1 = {a0.x - a2.x, a0.y - a2.y}, t2 = {a1.x + a3.x, a1.y + a3.y}, t3 = {a1.x - a3.x, a1.y - a3.y};
;   float2 b0 = {t0.x + t2.x, t0.y + t2.y}, b2 = {t0.x - t2.x, t0.y - t2.y}, b1 = {t1.x + t3.y, t1.y - t3.x}, b3 = {t1.x - t3.y, t1.y + t3.x};
;   const int Q = 1 << lq; const float invM = 1.f / (float)(4 << lq);
;   for (int bb = tid; bb < NBT * (N / 4); bb += NTHR) { const int b = bb & (N / 4 - 1); float2* z = z0 + (bb / (N / 4)) * N; int j = b & (Q - 1), base = ((b >> lq) << (lq + 2)) + j; float2 o0, o1, o2, o3;
;     bfly_fwd(z[base], z[base + Q], z[base + 2 * Q], z[base + 3 * Q], (float)j * invM, o0, o1, o2, o3);
;     z[base] = o0; z[base + Q] = o1; z[base + 2 * Q] = o2; z[base + 3 * Q] = o3; }
;   __syncthreads();
; }
.LBB0_1641:
	v_ashrrev_i32_e32 v6, 31, v5
	v_lshrrev_b32_e32 v6, 20, v6
	v_add_lshl_u32 v6, v5, v6, 5
	v_and_b32_e32 v7, 0x3ffc, v4
	v_and_b32_e32 v6, 0xfffe0000, v6
	v_lshlrev_b32_e32 v7, 3, v7
	v_add3_u32 v19, 16, v6, v7
	v_add_u32_e32 v204, 0x10000, v19
	ds_read_b128 v[6:9], v19
	ds_read_b128 v[10:13], v19 offset:16
	ds_read_b128 v[188:191], v19 offset:16384
	ds_read_b128 v[192:195], v19 offset:16400
	ds_read_b128 v[196:199], v19 offset:32768
	ds_read_b128 v[200:203], v19 offset:32784
	s_waitcnt lgkmcnt(4)
	v_pk_add_f32 v[14:15], v[6:7], v[10:11]
	v_pk_add_f32 v[22:23], v[8:9], v[12:13]
	v_pk_add_f32 v[20:21], v[6:7], v[10:11] neg_lo:[0,1] neg_hi:[0,1]
	v_pk_add_f32 v[24:25], v[8:9], v[12:13] neg_lo:[0,1] neg_hi:[0,1]
	v_pk_add_f32 v[6:7], v[14:15], v[22:23]
	v_pk_add_f32 v[10:11], v[14:15], v[22:23] neg_lo:[0,1] neg_hi:[0,1]
	v_pk_add_f32 v[8:9], v[20:21], v[24:25] op_sel:[0,1] op_sel_hi:[1,0] neg_hi:[0,1]
	v_pk_add_f32 v[12:13], v[20:21], v[24:25] op_sel:[0,1] op_sel_hi:[1,0] neg_lo:[0,1]
	s_nop 0
	ds_write_b128 v19, v[6:9]
	ds_write_b128 v19, v[10:13] offset:16
	ds_read_b128 v[6:9], v19 offset:49152
	ds_read_b128 v[10:13], v19 offset:49168
	s_waitcnt lgkmcnt(6)
	v_pk_add_f32 v[14:15], v[188:189], v[192:193]
	v_pk_add_f32 v[22:23], v[190:191], v[194:195]
	v_pk_add_f32 v[20:21], v[188:189], v[192:193] neg_lo:[0,1] neg_hi:[0,1]
	v_pk_add_f32 v[24:25], v[190:191], v[194:195] neg_lo:[0,1] neg_hi:[0,1]
	v_pk_add_f32 v[188:189], v[14:15], v[22:23]
	v_pk_add_f32 v[192:193], v[14:15], v[22:23] neg_lo:[0,1] neg_hi:[0,1]
	v_pk_add_f32 v[190:191], v[20:21], v[24:25] op_sel:[0,1] op_sel_hi:[1,0] neg_hi:[0,1]
	v_pk_add_f32 v[194:195], v[20:21], v[24:25] op_sel:[0,1] op_sel_hi:[1,0] neg_lo:[0,1]
	s_nop 0
	ds_write_b128 v19, v[188:191] offset:16384
	ds_write_b128 v19, v[192:195] offset:16400
	ds_read_b128 v[188:191], v204
	ds_read_b128 v[192:195], v204 offset:16
	s_waitcnt lgkmcnt(8)
	v_pk_add_f32 v[14:15], v[196:197], v[200:201]
	v_pk_add_f32 v[22:23], v[198:199], v[202:203]
	v_pk_add_f32 v[20:21], v[196:197], v[200:201] neg_lo:[0,1] neg_hi:[0,1]
	v_pk_add_f32 v[24:25], v[198:199], v[202:203] neg_lo:[0,1] neg_hi:[0,1]
	v_pk_add_f32 v[196:197], v[14:15], v[22:23]
	v_pk_add_f32 v[200:201], v[14:15], v[22:23] neg_lo:[0,1] neg_hi:[0,1]
	v_pk_add_f32 v[198:199], v[20:21], v[24:25] op_sel:[0,1] op_sel_hi:[1,0] neg_hi:[0,1]
	v_pk_add_f32 v[202:203], v[20:21], v[24:25] op_sel:[0,1] op_sel_hi:[1,0] neg_lo:[0,1]
	s_nop 0
	ds_write_b128 v19, v[196:199] offset:32768
	ds_write_b128 v19, v[200:203] offset:32784
	ds_read_b128 v[196:199], v204 offset:16384
	ds_read_b128 v[200:203], v204 offset:16400
	s_waitcnt lgkmcnt(8)
	v_pk_add_f32 v[14:15], v[6:7], v[10:11]
	v_pk_add_f32 v[22:23], v[8:9], v[12:13]
	v_pk_add_f32 v[20:21], v[6:7], v[10:11] neg_lo:[0,1] neg_hi:[0,1]
	v_pk_add_f32 v[24:25], v[8:9], v[12:13] neg_lo:[0,1] neg_hi:[0,1]
	v_pk_add_f32 v[6:7], v[14:15], v[22:23]
	v_pk_add_f32 v[10:11], v[14:15], v[22:23] neg_lo:[0,1] neg_hi:[0,1]
	v_pk_add_f32 v[8:9], v[20:21], v[24:25] op_sel:[0,1] op_sel_hi:[1,0] neg_hi:[0,1]
	v_pk_add_f32 v[12:13], v[20:21], v[24:25] op_sel:[0,1] op_sel_hi:[1,0] neg_lo:[0,1]
	s_nop 0
	ds_write_b128 v19, v[6:9] offset:49152
	ds_write_b128 v19, v[10:13] offset:49168
	ds_read_b128 v[6:9], v204 offset:32768
	ds_read_b128 v[10:13], v204 offset:32784
	s_waitcnt lgkmcnt(8)
	v_pk_add_f32 v[14:15], v[188:189], v[192:193]
	v_pk_add_f32 v[22:23], v[190:191], v[194:195]
	v_pk_add_f32 v[20:21], v[188:189], v[192:193] neg_lo:[0,1] neg_hi:[0,1]
	v_pk_add_f32 v[24:25], v[190:191], v[194:195] neg_lo:[0,1] neg_hi:[0,1]
	v_pk_add_f32 v[188:189], v[14:15], v[22:23]
	v_pk_add_f32 v[192:193], v[14:15], v[22:23] neg_lo:[0,1] neg_hi:[0,1]
	v_pk_add_f32 v[190:191], v[20:21], v[24:25] op_sel:[0,1] op_sel_hi:[1,0] neg_hi:[0,1]
	v_pk_add_f32 v[194:195], v[20:21], v[24:25] op_sel:[0,1] op_sel_hi:[1,0] neg_lo:[0,1]
	s_nop 0
	ds_write_b128 v204, v[188:191]
	ds_write_b128 v204, v[192:195] offset:16
	ds_read_b128 v[188:191], v204 offset:49152
	ds_read_b128 v[192:195], v204 offset:49168
	s_waitcnt lgkmcnt(8)
	v_pk_add_f32 v[14:15], v[196:197], v[200:201]
	v_pk_add_f32 v[22:23], v[198:199], v[202:203]
	v_pk_add_f32 v[20:21], v[196:197], v[200:201] neg_lo:[0,1] neg_hi:[0,1]
	v_pk_add_f32 v[24:25], v[198:199], v[202:203] neg_lo:[0,1] neg_hi:[0,1]
	v_pk_add_f32 v[196:197], v[14:15], v[22:23]
	v_pk_add_f32 v[200:201], v[14:15], v[22:23] neg_lo:[0,1] neg_hi:[0,1]
	v_pk_add_f32 v[198:199], v[20:21], v[24:25] op_sel:[0,1] op_sel_hi:[1,0] neg_hi:[0,1]
	v_pk_add_f32 v[202:203], v[20:21], v[24:25] op_sel:[0,1] op_sel_hi:[1,0] neg_lo:[0,1]
	s_nop 0
	ds_write_b128 v204, v[196:199] offset:16384
	ds_write_b128 v204, v[200:203] offset:16400
	s_waitcnt lgkmcnt(6)
	v_pk_add_f32 v[14:15], v[6:7], v[10:11]
	v_pk_add_f32 v[22:23], v[8:9], v[12:13]
	v_pk_add_f32 v[20:21], v[6:7], v[10:11] neg_lo:[0,1] neg_hi:[0,1]
	v_pk_add_f32 v[24:25], v[8:9], v[12:13] neg_lo:[0,1] neg_hi:[0,1]
	v_pk_add_f32 v[6:7], v[14:15], v[22:23]
	v_pk_add_f32 v[10:11], v[14:15], v[22:23] neg_lo:[0,1] neg_hi:[0,1]
	v_pk_add_f32 v[8:9], v[20:21], v[24:25] op_sel:[0,1] op_sel_hi:[1,0] neg_hi:[0,1]
	v_pk_add_f32 v[12:13], v[20:21], v[24:25] op_sel:[0,1] op_sel_hi:[1,0] neg_lo:[0,1]
	s_nop 0
	ds_write_b128 v204, v[6:9] offset:32768
	ds_write_b128 v204, v[10:13] offset:32784
	s_waitcnt lgkmcnt(4)
	v_pk_add_f32 v[14:15], v[188:189], v[192:193]
	v_pk_add_f32 v[22:23], v[190:191], v[194:195]
	v_pk_add_f32 v[20:21], v[188:189], v[192:193] neg_lo:[0,1] neg_hi:[0,1]
	v_pk_add_f32 v[24:25], v[190:191], v[194:195] neg_lo:[0,1] neg_hi:[0,1]
	v_pk_add_f32 v[188:189], v[14:15], v[22:23]
	v_pk_add_f32 v[192:193], v[14:15], v[22:23] neg_lo:[0,1] neg_hi:[0,1]
	v_pk_add_f32 v[190:191], v[20:21], v[24:25] op_sel:[0,1] op_sel_hi:[1,0] neg_hi:[0,1]
	v_pk_add_f32 v[194:195], v[20:21], v[24:25] op_sel:[0,1] op_sel_hi:[1,0] neg_lo:[0,1]
	s_nop 0
	ds_write_b128 v204, v[188:191] offset:49152
	ds_write_b128 v204, v[192:195] offset:49168
	v_add_u32_e32 v4, 0x4000, v4
	v_add_u32_e32 v6, 0x1000, v5
	v_mov_b32_e32 v5, v6
	s_mov_b64 s[80:81], exec
